# mLSTM gate_carry (serial 128-step recurrence ahead of the mLSTM in-projection GEMM on 16 workgroups) unrolled with immediate-lane readlane and lane-deposited results, three vector stores instead of 14
# speedup vs baseline: 1.0012x; 1.0012x over previous
.LBB0_875:
	s_cmp_lt_i32 s62, 10
	s_cselect_b64 s[0:1], -1, 0
	s_cmp_gt_i32 s63, 9
	s_cselect_b64 s[2:3], -1, 0
	s_and_b64 s[0:1], s[0:1], s[2:3]
	s_andn2_b64 vcc, exec, s[0:1]
	s_cbranch_vccnz .LBB0_1044
	s_cmp_lt_i32 s84, 16
	s_cselect_b64 s[0:1], -1, 0
	s_cmp_lt_u32 s85, 64
	s_cselect_b64 s[2:3], -1, 0
	s_and_b64 s[0:1], s[0:1], s[2:3]
	v_mov_b32_e32 v0, v212
	s_andn2_b64 vcc, exec, s[0:1]
	s_cbranch_vccnz .LBB0_889
	s_lshl_b32 s0, s84, 7
	v_and_b32_e32 v0, 63, v0
	s_add_i32 s1, s0, 0x62000
	v_or_b32_e32 v2, s1, v0
	s_waitcnt lgkmcnt(0)
	v_ashrrev_i32_e32 v3, 31, v2
	s_add_i32 s1, s0, 0x62040
	v_lshl_add_u64 v[6:7], v[2:3], 2, s[48:49]
	v_or_b32_e32 v2, s1, v0
	v_ashrrev_i32_e32 v3, 31, v2
	s_add_i32 s1, s0, 0x63000
	v_lshl_add_u64 v[8:9], v[2:3], 2, s[48:49]
	v_or_b32_e32 v2, s1, v0
	v_ashrrev_i32_e32 v3, 31, v2
	s_add_i32 s0, s0, 0x63040
	v_lshl_add_u64 v[10:11], v[2:3], 2, s[48:49]
	v_or_b32_e32 v2, s0, v0
	v_ashrrev_i32_e32 v3, 31, v2
	v_lshl_add_u64 v[12:13], v[2:3], 2, s[48:49]
	global_load_dword v1, v[6:7], off
	global_load_dword v2, v[8:9], off
	global_load_dword v3, v[10:11], off
	global_load_dword v4, v[12:13], off
	s_lshl_b32 s5, s84, 4
	s_mov_b32 s11, 0
	v_cmp_ne_u32_e32 vcc, 0, v0
	v_cmp_eq_u32_e64 s[0:1], 0, v0
	s_mul_i32 s4, s84, 0x81
	s_add_i32 s5, s5, 0x61000
	v_mov_b32_e32 v5, 0
	v_mov_b32_e32 v8, 0
	v_mov_b32_e32 v9, 0
	s_mov_b32 s8, 0x3fb8aa3b
	s_mov_b32 s9, 0xc2ce8ed0
	s_mov_b32 s10, 0x42b17218
	v_mov_b32_e32 v6, 0x7f800000
	v_mov_b32_e32 v7, 0
	s_waitcnt vmcnt(0)
	v_mov_b32_e32 v20, 0
	v_mov_b32_e32 v21, 0
	v_mov_b32_e32 v22, 0
	v_readlane_b32 s6, v1, 0
	v_readlane_b32 s7, v3, 0
	v_readfirstlane_b32 s12, v7
	v_add_f32_e32 v8, s6, v8
	v_max_f32_e32 v7, s7, v7
	v_writelane_b32 v20, s12, 0
	v_add_f32_e32 v7, s6, v7
	v_readlane_b32 s6, v1, 1
	v_readlane_b32 s7, v3, 1
	v_readfirstlane_b32 s12, v7
	v_add_f32_e32 v8, s6, v8
	v_max_f32_e32 v7, s7, v7
	v_writelane_b32 v20, s12, 1
	v_add_f32_e32 v7, s6, v7
	v_readlane_b32 s6, v1, 2
	v_readlane_b32 s7, v3, 2
	v_readfirstlane_b32 s12, v7
	v_add_f32_e32 v8, s6, v8
	v_max_f32_e32 v7, s7, v7
	v_writelane_b32 v20, s12, 2
	v_add_f32_e32 v7, s6, v7
	v_readlane_b32 s6, v1, 3
	v_readlane_b32 s7, v3, 3
	v_readfirstlane_b32 s12, v7
	v_add_f32_e32 v8, s6, v8
	v_max_f32_e32 v7, s7, v7
	v_writelane_b32 v20, s12, 3
	v_add_f32_e32 v7, s6, v7
	v_readlane_b32 s6, v1, 4
	v_readlane_b32 s7, v3, 4
	v_readfirstlane_b32 s12, v7
	v_add_f32_e32 v8, s6, v8
	v_max_f32_e32 v7, s7, v7
	v_writelane_b32 v20, s12, 4
	v_add_f32_e32 v7, s6, v7
	v_readlane_b32 s6, v1, 5
	v_readlane_b32 s7, v3, 5
	v_readfirstlane_b32 s12, v7
	v_add_f32_e32 v8, s6, v8
	v_max_f32_e32 v7, s7, v7
	v_writelane_b32 v20, s12, 5
	v_add_f32_e32 v7, s6, v7
	v_readlane_b32 s6, v1, 6
	v_readlane_b32 s7, v3, 6
	v_readfirstlane_b32 s12, v7
	v_add_f32_e32 v8, s6, v8
	v_max_f32_e32 v7, s7, v7
	v_writelane_b32 v20, s12, 6
	v_add_f32_e32 v7, s6, v7
	v_readlane_b32 s6, v1, 7
	v_readlane_b32 s7, v3, 7
	v_readfirstlane_b32 s12, v7
	v_add_f32_e32 v8, s6, v8
	v_max_f32_e32 v7, s7, v7
	v_writelane_b32 v20, s12, 7
	v_add_f32_e32 v7, s6, v7
	v_add_f32_e32 v10, v9, v8
	v_sub_f32_e32 v11, v10, v7
	v_mul_f32_e32 v10, 0x3fb8aa3b, v11
	v_fma_f32 v12, v11, s8, -v10
	v_rndne_f32_e32 v13, v10
	v_fmac_f32_e32 v12, 0x32a5705f, v11
	v_sub_f32_e32 v10, v10, v13
	v_add_f32_e32 v10, v10, v12
	v_cvt_i32_f32_e32 v12, v13
	v_exp_f32_e32 v10, v10
	v_cmp_ngt_f32_e64 s[2:3], s9, v11
	v_ldexp_f32 v12, v10, v12
	s_nop 0
	v_cndmask_b32_e64 v12, 0, v12, s[2:3]
	v_cmp_nlt_f32_e64 s[2:3], s10, v11
	v_mov_b32_e32 v8, 0
	s_nop 0
	v_cndmask_b32_e64 v10, v6, v12, s[2:3]
	v_mov_b32_e32 v9, v7
	s_nop 0
	v_readfirstlane_b32 s13, v10
	s_nop 1
	v_writelane_b32 v22, s13, 0
	v_readlane_b32 s6, v1, 8
	v_readlane_b32 s7, v3, 8
	v_readfirstlane_b32 s12, v7
	v_add_f32_e32 v8, s6, v8
	v_max_f32_e32 v7, s7, v7
	v_writelane_b32 v20, s12, 8
	v_add_f32_e32 v7, s6, v7
	v_readlane_b32 s6, v1, 9
	v_readlane_b32 s7, v3, 9
	v_readfirstlane_b32 s12, v7
	v_add_f32_e32 v8, s6, v8
	v_max_f32_e32 v7, s7, v7
	v_writelane_b32 v20, s12, 9
	v_add_f32_e32 v7, s6, v7
	v_readlane_b32 s6, v1, 10
	v_readlane_b32 s7, v3, 10
	v_readfirstlane_b32 s12, v7
	v_add_f32_e32 v8, s6, v8
	v_max_f32_e32 v7, s7, v7
	v_writelane_b32 v20, s12, 10
	v_add_f32_e32 v7, s6, v7
	v_readlane_b32 s6, v1, 11
	v_readlane_b32 s7, v3, 11
	v_readfirstlane_b32 s12, v7
	v_add_f32_e32 v8, s6, v8
	v_max_f32_e32 v7, s7, v7
	v_writelane_b32 v20, s12, 11
	v_add_f32_e32 v7, s6, v7
	v_readlane_b32 s6, v1, 12
	v_readlane_b32 s7, v3, 12
	v_readfirstlane_b32 s12, v7
	v_add_f32_e32 v8, s6, v8
	v_max_f32_e32 v7, s7, v7
	v_writelane_b32 v20, s12, 12
	v_add_f32_e32 v7, s6, v7
	v_readlane_b32 s6, v1, 13
	v_readlane_b32 s7, v3, 13
	v_readfirstlane_b32 s12, v7
	v_add_f32_e32 v8, s6, v8
	v_max_f32_e32 v7, s7, v7
	v_writelane_b32 v20, s12, 13
	v_add_f32_e32 v7, s6, v7
	v_readlane_b32 s6, v1, 14
	v_readlane_b32 s7, v3, 14
	v_readfirstlane_b32 s12, v7
	v_add_f32_e32 v8, s6, v8
	v_max_f32_e32 v7, s7, v7
	v_writelane_b32 v20, s12, 14
	v_add_f32_e32 v7, s6, v7
	v_readlane_b32 s6, v1, 15
	v_readlane_b32 s7, v3, 15
	v_readfirstlane_b32 s12, v7
	v_add_f32_e32 v8, s6, v8
	v_max_f32_e32 v7, s7, v7
	v_writelane_b32 v20, s12, 15
	v_add_f32_e32 v7, s6, v7
	v_add_f32_e32 v10, v9, v8
	v_sub_f32_e32 v11, v10, v7
	v_mul_f32_e32 v10, 0x3fb8aa3b, v11
	v_fma_f32 v12, v11, s8, -v10
	v_rndne_f32_e32 v13, v10
	v_fmac_f32_e32 v12, 0x32a5705f, v11
	v_sub_f32_e32 v10, v10, v13
	v_add_f32_e32 v10, v10, v12
	v_cvt_i32_f32_e32 v12, v13
	v_exp_f32_e32 v10, v10
	v_cmp_ngt_f32_e64 s[2:3], s9, v11
	v_ldexp_f32 v12, v10, v12
	s_nop 0
	v_cndmask_b32_e64 v12, 0, v12, s[2:3]
	v_cmp_nlt_f32_e64 s[2:3], s10, v11
	v_mov_b32_e32 v8, 0
	s_nop 0
	v_cndmask_b32_e64 v10, v6, v12, s[2:3]
	v_mov_b32_e32 v9, v7
	s_nop 0
	v_readfirstlane_b32 s13, v10
	s_nop 1
	v_writelane_b32 v22, s13, 1
	v_readlane_b32 s6, v1, 16
	v_readlane_b32 s7, v3, 16
	v_readfirstlane_b32 s12, v7
	v_add_f32_e32 v8, s6, v8
	v_max_f32_e32 v7, s7, v7
	v_writelane_b32 v20, s12, 16
	v_add_f32_e32 v7, s6, v7
	v_readlane_b32 s6, v1, 17
	v_readlane_b32 s7, v3, 17
	v_readfirstlane_b32 s12, v7
	v_add_f32_e32 v8, s6, v8
	v_max_f32_e32 v7, s7, v7
	v_writelane_b32 v20, s12, 17
	v_add_f32_e32 v7, s6, v7
	v_readlane_b32 s6, v1, 18
	v_readlane_b32 s7, v3, 18
	v_readfirstlane_b32 s12, v7
	v_add_f32_e32 v8, s6, v8
	v_max_f32_e32 v7, s7, v7
	v_writelane_b32 v20, s12, 18
	v_add_f32_e32 v7, s6, v7
	v_readlane_b32 s6, v1, 19
	v_readlane_b32 s7, v3, 19
	v_readfirstlane_b32 s12, v7
	v_add_f32_e32 v8, s6, v8
	v_max_f32_e32 v7, s7, v7
	v_writelane_b32 v20, s12, 19
	v_add_f32_e32 v7, s6, v7
	v_readlane_b32 s6, v1, 20
	v_readlane_b32 s7, v3, 20
	v_readfirstlane_b32 s12, v7
	v_add_f32_e32 v8, s6, v8
	v_max_f32_e32 v7, s7, v7
	v_writelane_b32 v20, s12, 20
	v_add_f32_e32 v7, s6, v7
	v_readlane_b32 s6, v1, 21
	v_readlane_b32 s7, v3, 21
	v_readfirstlane_b32 s12, v7
	v_add_f32_e32 v8, s6, v8
	v_max_f32_e32 v7, s7, v7
	v_writelane_b32 v20, s12, 21
	v_add_f32_e32 v7, s6, v7
	v_readlane_b32 s6, v1, 22
	v_readlane_b32 s7, v3, 22
	v_readfirstlane_b32 s12, v7
	v_add_f32_e32 v8, s6, v8
	v_max_f32_e32 v7, s7, v7
	v_writelane_b32 v20, s12, 22
	v_add_f32_e32 v7, s6, v7
	v_readlane_b32 s6, v1, 23
	v_readlane_b32 s7, v3, 23
	v_readfirstlane_b32 s12, v7
	v_add_f32_e32 v8, s6, v8
	v_max_f32_e32 v7, s7, v7
	v_writelane_b32 v20, s12, 23
	v_add_f32_e32 v7, s6, v7
	v_add_f32_e32 v10, v9, v8
	v_sub_f32_e32 v11, v10, v7
	v_mul_f32_e32 v10, 0x3fb8aa3b, v11
	v_fma_f32 v12, v11, s8, -v10
	v_rndne_f32_e32 v13, v10
	v_fmac_f32_e32 v12, 0x32a5705f, v11
	v_sub_f32_e32 v10, v10, v13
	v_add_f32_e32 v10, v10, v12
	v_cvt_i32_f32_e32 v12, v13
	v_exp_f32_e32 v10, v10
	v_cmp_ngt_f32_e64 s[2:3], s9, v11
	v_ldexp_f32 v12, v10, v12
	s_nop 0
	v_cndmask_b32_e64 v12, 0, v12, s[2:3]
	v_cmp_nlt_f32_e64 s[2:3], s10, v11
	v_mov_b32_e32 v8, 0
	s_nop 0
	v_cndmask_b32_e64 v10, v6, v12, s[2:3]
	v_mov_b32_e32 v9, v7
	s_nop 0
	v_readfirstlane_b32 s13, v10
	s_nop 1
	v_writelane_b32 v22, s13, 2
	v_readlane_b32 s6, v1, 24
	v_readlane_b32 s7, v3, 24
	v_readfirstlane_b32 s12, v7
	v_add_f32_e32 v8, s6, v8
	v_max_f32_e32 v7, s7, v7
	v_writelane_b32 v20, s12, 24
	v_add_f32_e32 v7, s6, v7
	v_readlane_b32 s6, v1, 25
	v_readlane_b32 s7, v3, 25
	v_readfirstlane_b32 s12, v7
	v_add_f32_e32 v8, s6, v8
	v_max_f32_e32 v7, s7, v7
	v_writelane_b32 v20, s12, 25
	v_add_f32_e32 v7, s6, v7
	v_readlane_b32 s6, v1, 26
	v_readlane_b32 s7, v3, 26
	v_readfirstlane_b32 s12, v7
	v_add_f32_e32 v8, s6, v8
	v_max_f32_e32 v7, s7, v7
	v_writelane_b32 v20, s12, 26
	v_add_f32_e32 v7, s6, v7
	v_readlane_b32 s6, v1, 27
	v_readlane_b32 s7, v3, 27
	v_readfirstlane_b32 s12, v7
	v_add_f32_e32 v8, s6, v8
	v_max_f32_e32 v7, s7, v7
	v_writelane_b32 v20, s12, 27
	v_add_f32_e32 v7, s6, v7
	v_readlane_b32 s6, v1, 28
	v_readlane_b32 s7, v3, 28
	v_readfirstlane_b32 s12, v7
	v_add_f32_e32 v8, s6, v8
	v_max_f32_e32 v7, s7, v7
	v_writelane_b32 v20, s12, 28
	v_add_f32_e32 v7, s6, v7
	v_readlane_b32 s6, v1, 29
	v_readlane_b32 s7, v3, 29
	v_readfirstlane_b32 s12, v7
	v_add_f32_e32 v8, s6, v8
	v_max_f32_e32 v7, s7, v7
	v_writelane_b32 v20, s12, 29
	v_add_f32_e32 v7, s6, v7
	v_readlane_b32 s6, v1, 30
	v_readlane_b32 s7, v3, 30
	v_readfirstlane_b32 s12, v7
	v_add_f32_e32 v8, s6, v8
	v_max_f32_e32 v7, s7, v7
	v_writelane_b32 v20, s12, 30
	v_add_f32_e32 v7, s6, v7
	v_readlane_b32 s6, v1, 31
	v_readlane_b32 s7, v3, 31
	v_readfirstlane_b32 s12, v7
	v_add_f32_e32 v8, s6, v8
	v_max_f32_e32 v7, s7, v7
	v_writelane_b32 v20, s12, 31
	v_add_f32_e32 v7, s6, v7
	v_add_f32_e32 v10, v9, v8
	v_sub_f32_e32 v11, v10, v7
	v_mul_f32_e32 v10, 0x3fb8aa3b, v11
	v_fma_f32 v12, v11, s8, -v10
	v_rndne_f32_e32 v13, v10
	v_fmac_f32_e32 v12, 0x32a5705f, v11
	v_sub_f32_e32 v10, v10, v13
	v_add_f32_e32 v10, v10, v12
	v_cvt_i32_f32_e32 v12, v13
	v_exp_f32_e32 v10, v10
	v_cmp_ngt_f32_e64 s[2:3], s9, v11
	v_ldexp_f32 v12, v10, v12
	s_nop 0
	v_cndmask_b32_e64 v12, 0, v12, s[2:3]
	v_cmp_nlt_f32_e64 s[2:3], s10, v11
	v_mov_b32_e32 v8, 0
	s_nop 0
	v_cndmask_b32_e64 v10, v6, v12, s[2:3]
	v_mov_b32_e32 v9, v7
	s_nop 0
	v_readfirstlane_b32 s13, v10
	s_nop 1
	v_writelane_b32 v22, s13, 3
	v_readlane_b32 s6, v1, 32
	v_readlane_b32 s7, v3, 32
	v_readfirstlane_b32 s12, v7
	v_add_f32_e32 v8, s6, v8
	v_max_f32_e32 v7, s7, v7
	v_writelane_b32 v20, s12, 32
	v_add_f32_e32 v7, s6, v7
	v_readlane_b32 s6, v1, 33
	v_readlane_b32 s7, v3, 33
	v_readfirstlane_b32 s12, v7
	v_add_f32_e32 v8, s6, v8
	v_max_f32_e32 v7, s7, v7
	v_writelane_b32 v20, s12, 33
	v_add_f32_e32 v7, s6, v7
	v_readlane_b32 s6, v1, 34
	v_readlane_b32 s7, v3, 34
	v_readfirstlane_b32 s12, v7
	v_add_f32_e32 v8, s6, v8
	v_max_f32_e32 v7, s7, v7
	v_writelane_b32 v20, s12, 34
	v_add_f32_e32 v7, s6, v7
	v_readlane_b32 s6, v1, 35
	v_readlane_b32 s7, v3, 35
	v_readfirstlane_b32 s12, v7
	v_add_f32_e32 v8, s6, v8
	v_max_f32_e32 v7, s7, v7
	v_writelane_b32 v20, s12, 35
	v_add_f32_e32 v7, s6, v7
	v_readlane_b32 s6, v1, 36
	v_readlane_b32 s7, v3, 36
	v_readfirstlane_b32 s12, v7
	v_add_f32_e32 v8, s6, v8
	v_max_f32_e32 v7, s7, v7
	v_writelane_b32 v20, s12, 36
	v_add_f32_e32 v7, s6, v7
	v_readlane_b32 s6, v1, 37
	v_readlane_b32 s7, v3, 37
	v_readfirstlane_b32 s12, v7
	v_add_f32_e32 v8, s6, v8
	v_max_f32_e32 v7, s7, v7
	v_writelane_b32 v20, s12, 37
	v_add_f32_e32 v7, s6, v7
	v_readlane_b32 s6, v1, 38
	v_readlane_b32 s7, v3, 38
	v_readfirstlane_b32 s12, v7
	v_add_f32_e32 v8, s6, v8
	v_max_f32_e32 v7, s7, v7
	v_writelane_b32 v20, s12, 38
	v_add_f32_e32 v7, s6, v7
	v_readlane_b32 s6, v1, 39
	v_readlane_b32 s7, v3, 39
	v_readfirstlane_b32 s12, v7
	v_add_f32_e32 v8, s6, v8
	v_max_f32_e32 v7, s7, v7
	v_writelane_b32 v20, s12, 39
	v_add_f32_e32 v7, s6, v7
	v_add_f32_e32 v10, v9, v8
	v_sub_f32_e32 v11, v10, v7
	v_mul_f32_e32 v10, 0x3fb8aa3b, v11
	v_fma_f32 v12, v11, s8, -v10
	v_rndne_f32_e32 v13, v10
	v_fmac_f32_e32 v12, 0x32a5705f, v11
	v_sub_f32_e32 v10, v10, v13
	v_add_f32_e32 v10, v10, v12
	v_cvt_i32_f32_e32 v12, v13
	v_exp_f32_e32 v10, v10
	v_cmp_ngt_f32_e64 s[2:3], s9, v11
	v_ldexp_f32 v12, v10, v12
	s_nop 0
	v_cndmask_b32_e64 v12, 0, v12, s[2:3]
	v_cmp_nlt_f32_e64 s[2:3], s10, v11
	v_mov_b32_e32 v8, 0
	s_nop 0
	v_cndmask_b32_e64 v10, v6, v12, s[2:3]
	v_mov_b32_e32 v9, v7
	s_nop 0
	v_readfirstlane_b32 s13, v10
	s_nop 1
	v_writelane_b32 v22, s13, 4
	v_readlane_b32 s6, v1, 40
	v_readlane_b32 s7, v3, 40
	v_readfirstlane_b32 s12, v7
	v_add_f32_e32 v8, s6, v8
	v_max_f32_e32 v7, s7, v7
	v_writelane_b32 v20, s12, 40
	v_add_f32_e32 v7, s6, v7
	v_readlane_b32 s6, v1, 41
	v_readlane_b32 s7, v3, 41
	v_readfirstlane_b32 s12, v7
	v_add_f32_e32 v8, s6, v8
	v_max_f32_e32 v7, s7, v7
	v_writelane_b32 v20, s12, 41
	v_add_f32_e32 v7, s6, v7
	v_readlane_b32 s6, v1, 42
	v_readlane_b32 s7, v3, 42
	v_readfirstlane_b32 s12, v7
	v_add_f32_e32 v8, s6, v8
	v_max_f32_e32 v7, s7, v7
	v_writelane_b32 v20, s12, 42
	v_add_f32_e32 v7, s6, v7
	v_readlane_b32 s6, v1, 43
	v_readlane_b32 s7, v3, 43
	v_readfirstlane_b32 s12, v7
	v_add_f32_e32 v8, s6, v8
	v_max_f32_e32 v7, s7, v7
	v_writelane_b32 v20, s12, 43
	v_add_f32_e32 v7, s6, v7
	v_readlane_b32 s6, v1, 44
	v_readlane_b32 s7, v3, 44
	v_readfirstlane_b32 s12, v7
	v_add_f32_e32 v8, s6, v8
	v_max_f32_e32 v7, s7, v7
	v_writelane_b32 v20, s12, 44
	v_add_f32_e32 v7, s6, v7
	v_readlane_b32 s6, v1, 45
	v_readlane_b32 s7, v3, 45
	v_readfirstlane_b32 s12, v7
	v_add_f32_e32 v8, s6, v8
	v_max_f32_e32 v7, s7, v7
	v_writelane_b32 v20, s12, 45
	v_add_f32_e32 v7, s6, v7
	v_readlane_b32 s6, v1, 46
	v_readlane_b32 s7, v3, 46
	v_readfirstlane_b32 s12, v7
	v_add_f32_e32 v8, s6, v8
	v_max_f32_e32 v7, s7, v7
	v_writelane_b32 v20, s12, 46
	v_add_f32_e32 v7, s6, v7
	v_readlane_b32 s6, v1, 47
	v_readlane_b32 s7, v3, 47
	v_readfirstlane_b32 s12, v7
	v_add_f32_e32 v8, s6, v8
	v_max_f32_e32 v7, s7, v7
	v_writelane_b32 v20, s12, 47
	v_add_f32_e32 v7, s6, v7
	v_add_f32_e32 v10, v9, v8
	v_sub_f32_e32 v11, v10, v7
	v_mul_f32_e32 v10, 0x3fb8aa3b, v11
	v_fma_f32 v12, v11, s8, -v10
	v_rndne_f32_e32 v13, v10
	v_fmac_f32_e32 v12, 0x32a5705f, v11
	v_sub_f32_e32 v10, v10, v13
	v_add_f32_e32 v10, v10, v12
	v_cvt_i32_f32_e32 v12, v13
	v_exp_f32_e32 v10, v10
	v_cmp_ngt_f32_e64 s[2:3], s9, v11
	v_ldexp_f32 v12, v10, v12
	s_nop 0
	v_cndmask_b32_e64 v12, 0, v12, s[2:3]
	v_cmp_nlt_f32_e64 s[2:3], s10, v11
	v_mov_b32_e32 v8, 0
	s_nop 0
	v_cndmask_b32_e64 v10, v6, v12, s[2:3]
	v_mov_b32_e32 v9, v7
	s_nop 0
	v_readfirstlane_b32 s13, v10
	s_nop 1
	v_writelane_b32 v22, s13, 5
	v_readlane_b32 s6, v1, 48
	v_readlane_b32 s7, v3, 48
	v_readfirstlane_b32 s12, v7
	v_add_f32_e32 v8, s6, v8
	v_max_f32_e32 v7, s7, v7
	v_writelane_b32 v20, s12, 48
	v_add_f32_e32 v7, s6, v7
	v_readlane_b32 s6, v1, 49
	v_readlane_b32 s7, v3, 49
	v_readfirstlane_b32 s12, v7
	v_add_f32_e32 v8, s6, v8
	v_max_f32_e32 v7, s7, v7
	v_writelane_b32 v20, s12, 49
	v_add_f32_e32 v7, s6, v7
	v_readlane_b32 s6, v1, 50
	v_readlane_b32 s7, v3, 50
	v_readfirstlane_b32 s12, v7
	v_add_f32_e32 v8, s6, v8
	v_max_f32_e32 v7, s7, v7
	v_writelane_b32 v20, s12, 50
	v_add_f32_e32 v7, s6, v7
	v_readlane_b32 s6, v1, 51
	v_readlane_b32 s7, v3, 51
	v_readfirstlane_b32 s12, v7
	v_add_f32_e32 v8, s6, v8
	v_max_f32_e32 v7, s7, v7
	v_writelane_b32 v20, s12, 51
	v_add_f32_e32 v7, s6, v7
	v_readlane_b32 s6, v1, 52
	v_readlane_b32 s7, v3, 52
	v_readfirstlane_b32 s12, v7
	v_add_f32_e32 v8, s6, v8
	v_max_f32_e32 v7, s7, v7
	v_writelane_b32 v20, s12, 52
	v_add_f32_e32 v7, s6, v7
	v_readlane_b32 s6, v1, 53
	v_readlane_b32 s7, v3, 53
	v_readfirstlane_b32 s12, v7
	v_add_f32_e32 v8, s6, v8
	v_max_f32_e32 v7, s7, v7
	v_writelane_b32 v20, s12, 53
	v_add_f32_e32 v7, s6, v7
	v_readlane_b32 s6, v1, 54
	v_readlane_b32 s7, v3, 54
	v_readfirstlane_b32 s12, v7
	v_add_f32_e32 v8, s6, v8
	v_max_f32_e32 v7, s7, v7
	v_writelane_b32 v20, s12, 54
	v_add_f32_e32 v7, s6, v7
	v_readlane_b32 s6, v1, 55
	v_readlane_b32 s7, v3, 55
	v_readfirstlane_b32 s12, v7
	v_add_f32_e32 v8, s6, v8
	v_max_f32_e32 v7, s7, v7
	v_writelane_b32 v20, s12, 55
	v_add_f32_e32 v7, s6, v7
	v_add_f32_e32 v10, v9, v8
	v_sub_f32_e32 v11, v10, v7
	v_mul_f32_e32 v10, 0x3fb8aa3b, v11
	v_fma_f32 v12, v11, s8, -v10
	v_rndne_f32_e32 v13, v10
	v_fmac_f32_e32 v12, 0x32a5705f, v11
	v_sub_f32_e32 v10, v10, v13
	v_add_f32_e32 v10, v10, v12
	v_cvt_i32_f32_e32 v12, v13
	v_exp_f32_e32 v10, v10
	v_cmp_ngt_f32_e64 s[2:3], s9, v11
	v_ldexp_f32 v12, v10, v12
	s_nop 0
	v_cndmask_b32_e64 v12, 0, v12, s[2:3]
	v_cmp_nlt_f32_e64 s[2:3], s10, v11
	v_mov_b32_e32 v8, 0
	s_nop 0
	v_cndmask_b32_e64 v10, v6, v12, s[2:3]
	v_mov_b32_e32 v9, v7
	s_nop 0
	v_readfirstlane_b32 s13, v10
	s_nop 1
	v_writelane_b32 v22, s13, 6
	v_readlane_b32 s6, v1, 56
	v_readlane_b32 s7, v3, 56
	v_readfirstlane_b32 s12, v7
	v_add_f32_e32 v8, s6, v8
	v_max_f32_e32 v7, s7, v7
	v_writelane_b32 v20, s12, 56
	v_add_f32_e32 v7, s6, v7
	v_readlane_b32 s6, v1, 57
	v_readlane_b32 s7, v3, 57
	v_readfirstlane_b32 s12, v7
	v_add_f32_e32 v8, s6, v8
	v_max_f32_e32 v7, s7, v7
	v_writelane_b32 v20, s12, 57
	v_add_f32_e32 v7, s6, v7
	v_readlane_b32 s6, v1, 58
	v_readlane_b32 s7, v3, 58
	v_readfirstlane_b32 s12, v7
	v_add_f32_e32 v8, s6, v8
	v_max_f32_e32 v7, s7, v7
	v_writelane_b32 v20, s12, 58
	v_add_f32_e32 v7, s6, v7
	v_readlane_b32 s6, v1, 59
	v_readlane_b32 s7, v3, 59
	v_readfirstlane_b32 s12, v7
	v_add_f32_e32 v8, s6, v8
	v_max_f32_e32 v7, s7, v7
	v_writelane_b32 v20, s12, 59
	v_add_f32_e32 v7, s6, v7
	v_readlane_b32 s6, v1, 60
	v_readlane_b32 s7, v3, 60
	v_readfirstlane_b32 s12, v7
	v_add_f32_e32 v8, s6, v8
	v_max_f32_e32 v7, s7, v7
	v_writelane_b32 v20, s12, 60
	v_add_f32_e32 v7, s6, v7
	v_readlane_b32 s6, v1, 61
	v_readlane_b32 s7, v3, 61
	v_readfirstlane_b32 s12, v7
	v_add_f32_e32 v8, s6, v8
	v_max_f32_e32 v7, s7, v7
	v_writelane_b32 v20, s12, 61
	v_add_f32_e32 v7, s6, v7
	v_readlane_b32 s6, v1, 62
	v_readlane_b32 s7, v3, 62
	v_readfirstlane_b32 s12, v7
	v_add_f32_e32 v8, s6, v8
	v_max_f32_e32 v7, s7, v7
	v_writelane_b32 v20, s12, 62
	v_add_f32_e32 v7, s6, v7
	v_readlane_b32 s6, v1, 63
	v_readlane_b32 s7, v3, 63
	v_readfirstlane_b32 s12, v7
	v_add_f32_e32 v8, s6, v8
	v_max_f32_e32 v7, s7, v7
	v_writelane_b32 v20, s12, 63
	v_add_f32_e32 v7, s6, v7
	v_add_f32_e32 v10, v9, v8
	v_sub_f32_e32 v11, v10, v7
	v_mul_f32_e32 v10, 0x3fb8aa3b, v11
	v_fma_f32 v12, v11, s8, -v10
	v_rndne_f32_e32 v13, v10
	v_fmac_f32_e32 v12, 0x32a5705f, v11
	v_sub_f32_e32 v10, v10, v13
	v_add_f32_e32 v10, v10, v12
	v_cvt_i32_f32_e32 v12, v13
	v_exp_f32_e32 v10, v10
	v_cmp_ngt_f32_e64 s[2:3], s9, v11
	v_ldexp_f32 v12, v10, v12
	s_nop 0
	v_cndmask_b32_e64 v12, 0, v12, s[2:3]
	v_cmp_nlt_f32_e64 s[2:3], s10, v11
	v_mov_b32_e32 v8, 0
	s_nop 0
	v_cndmask_b32_e64 v10, v6, v12, s[2:3]
	v_mov_b32_e32 v9, v7
	s_nop 0
	v_readfirstlane_b32 s13, v10
	s_nop 1
	v_writelane_b32 v22, s13, 7
	v_readlane_b32 s6, v2, 0
	v_readlane_b32 s7, v4, 0
	v_readfirstlane_b32 s12, v7
	v_add_f32_e32 v8, s6, v8
	v_max_f32_e32 v7, s7, v7
	v_writelane_b32 v21, s12, 0
	v_add_f32_e32 v7, s6, v7
	v_readlane_b32 s6, v2, 1
	v_readlane_b32 s7, v4, 1
	v_readfirstlane_b32 s12, v7
	v_add_f32_e32 v8, s6, v8
	v_max_f32_e32 v7, s7, v7
	v_writelane_b32 v21, s12, 1
	v_add_f32_e32 v7, s6, v7
	v_readlane_b32 s6, v2, 2
	v_readlane_b32 s7, v4, 2
	v_readfirstlane_b32 s12, v7
	v_add_f32_e32 v8, s6, v8
	v_max_f32_e32 v7, s7, v7
	v_writelane_b32 v21, s12, 2
	v_add_f32_e32 v7, s6, v7
	v_readlane_b32 s6, v2, 3
	v_readlane_b32 s7, v4, 3
	v_readfirstlane_b32 s12, v7
	v_add_f32_e32 v8, s6, v8
	v_max_f32_e32 v7, s7, v7
	v_writelane_b32 v21, s12, 3
	v_add_f32_e32 v7, s6, v7
	v_readlane_b32 s6, v2, 4
	v_readlane_b32 s7, v4, 4
	v_readfirstlane_b32 s12, v7
	v_add_f32_e32 v8, s6, v8
	v_max_f32_e32 v7, s7, v7
	v_writelane_b32 v21, s12, 4
	v_add_f32_e32 v7, s6, v7
	v_readlane_b32 s6, v2, 5
	v_readlane_b32 s7, v4, 5
	v_readfirstlane_b32 s12, v7
	v_add_f32_e32 v8, s6, v8
	v_max_f32_e32 v7, s7, v7
	v_writelane_b32 v21, s12, 5
	v_add_f32_e32 v7, s6, v7
	v_readlane_b32 s6, v2, 6
	v_readlane_b32 s7, v4, 6
	v_readfirstlane_b32 s12, v7
	v_add_f32_e32 v8, s6, v8
	v_max_f32_e32 v7, s7, v7
	v_writelane_b32 v21, s12, 6
	v_add_f32_e32 v7, s6, v7
	v_readlane_b32 s6, v2, 7
	v_readlane_b32 s7, v4, 7
	v_readfirstlane_b32 s12, v7
	v_add_f32_e32 v8, s6, v8
	v_max_f32_e32 v7, s7, v7
	v_writelane_b32 v21, s12, 7
	v_add_f32_e32 v7, s6, v7
	v_add_f32_e32 v10, v9, v8
	v_sub_f32_e32 v11, v10, v7
	v_mul_f32_e32 v10, 0x3fb8aa3b, v11
	v_fma_f32 v12, v11, s8, -v10
	v_rndne_f32_e32 v13, v10
	v_fmac_f32_e32 v12, 0x32a5705f, v11
	v_sub_f32_e32 v10, v10, v13
	v_add_f32_e32 v10, v10, v12
	v_cvt_i32_f32_e32 v12, v13
	v_exp_f32_e32 v10, v10
	v_cmp_ngt_f32_e64 s[2:3], s9, v11
	v_ldexp_f32 v12, v10, v12
	s_nop 0
	v_cndmask_b32_e64 v12, 0, v12, s[2:3]
	v_cmp_nlt_f32_e64 s[2:3], s10, v11
	v_mov_b32_e32 v8, 0
	s_nop 0
	v_cndmask_b32_e64 v10, v6, v12, s[2:3]
	v_mov_b32_e32 v9, v7
	s_nop 0
	v_readfirstlane_b32 s13, v10
	s_nop 1
	v_writelane_b32 v22, s13, 8
	v_readlane_b32 s6, v2, 8
	v_readlane_b32 s7, v4, 8
	v_readfirstlane_b32 s12, v7
	v_add_f32_e32 v8, s6, v8
	v_max_f32_e32 v7, s7, v7
	v_writelane_b32 v21, s12, 8
	v_add_f32_e32 v7, s6, v7
	v_readlane_b32 s6, v2, 9
	v_readlane_b32 s7, v4, 9
	v_readfirstlane_b32 s12, v7
	v_add_f32_e32 v8, s6, v8
	v_max_f32_e32 v7, s7, v7
	v_writelane_b32 v21, s12, 9
	v_add_f32_e32 v7, s6, v7
	v_readlane_b32 s6, v2, 10
	v_readlane_b32 s7, v4, 10
	v_readfirstlane_b32 s12, v7
	v_add_f32_e32 v8, s6, v8
	v_max_f32_e32 v7, s7, v7
	v_writelane_b32 v21, s12, 10
	v_add_f32_e32 v7, s6, v7
	v_readlane_b32 s6, v2, 11
	v_readlane_b32 s7, v4, 11
	v_readfirstlane_b32 s12, v7
	v_add_f32_e32 v8, s6, v8
	v_max_f32_e32 v7, s7, v7
	v_writelane_b32 v21, s12, 11
	v_add_f32_e32 v7, s6, v7
	v_readlane_b32 s6, v2, 12
	v_readlane_b32 s7, v4, 12
	v_readfirstlane_b32 s12, v7
	v_add_f32_e32 v8, s6, v8
	v_max_f32_e32 v7, s7, v7
	v_writelane_b32 v21, s12, 12
	v_add_f32_e32 v7, s6, v7
	v_readlane_b32 s6, v2, 13
	v_readlane_b32 s7, v4, 13
	v_readfirstlane_b32 s12, v7
	v_add_f32_e32 v8, s6, v8
	v_max_f32_e32 v7, s7, v7
	v_writelane_b32 v21, s12, 13
	v_add_f32_e32 v7, s6, v7
	v_readlane_b32 s6, v2, 14
	v_readlane_b32 s7, v4, 14
	v_readfirstlane_b32 s12, v7
	v_add_f32_e32 v8, s6, v8
	v_max_f32_e32 v7, s7, v7
	v_writelane_b32 v21, s12, 14
	v_add_f32_e32 v7, s6, v7
	v_readlane_b32 s6, v2, 15
	v_readlane_b32 s7, v4, 15
	v_readfirstlane_b32 s12, v7
	v_add_f32_e32 v8, s6, v8
	v_max_f32_e32 v7, s7, v7
	v_writelane_b32 v21, s12, 15
	v_add_f32_e32 v7, s6, v7
	v_add_f32_e32 v10, v9, v8
	v_sub_f32_e32 v11, v10, v7
	v_mul_f32_e32 v10, 0x3fb8aa3b, v11
	v_fma_f32 v12, v11, s8, -v10
	v_rndne_f32_e32 v13, v10
	v_fmac_f32_e32 v12, 0x32a5705f, v11
	v_sub_f32_e32 v10, v10, v13
	v_add_f32_e32 v10, v10, v12
	v_cvt_i32_f32_e32 v12, v13
	v_exp_f32_e32 v10, v10
	v_cmp_ngt_f32_e64 s[2:3], s9, v11
	v_ldexp_f32 v12, v10, v12
	s_nop 0
	v_cndmask_b32_e64 v12, 0, v12, s[2:3]
	v_cmp_nlt_f32_e64 s[2:3], s10, v11
	v_mov_b32_e32 v8, 0
	s_nop 0
	v_cndmask_b32_e64 v10, v6, v12, s[2:3]
	v_mov_b32_e32 v9, v7
	s_nop 0
	v_readfirstlane_b32 s13, v10
	s_nop 1
	v_writelane_b32 v22, s13, 9
	v_readlane_b32 s6, v2, 16
	v_readlane_b32 s7, v4, 16
	v_readfirstlane_b32 s12, v7
	v_add_f32_e32 v8, s6, v8
	v_max_f32_e32 v7, s7, v7
	v_writelane_b32 v21, s12, 16
	v_add_f32_e32 v7, s6, v7
	v_readlane_b32 s6, v2, 17
	v_readlane_b32 s7, v4, 17
	v_readfirstlane_b32 s12, v7
	v_add_f32_e32 v8, s6, v8
	v_max_f32_e32 v7, s7, v7
	v_writelane_b32 v21, s12, 17
	v_add_f32_e32 v7, s6, v7
	v_readlane_b32 s6, v2, 18
	v_readlane_b32 s7, v4, 18
	v_readfirstlane_b32 s12, v7
	v_add_f32_e32 v8, s6, v8
	v_max_f32_e32 v7, s7, v7
	v_writelane_b32 v21, s12, 18
	v_add_f32_e32 v7, s6, v7
	v_readlane_b32 s6, v2, 19
	v_readlane_b32 s7, v4, 19
	v_readfirstlane_b32 s12, v7
	v_add_f32_e32 v8, s6, v8
	v_max_f32_e32 v7, s7, v7
	v_writelane_b32 v21, s12, 19
	v_add_f32_e32 v7, s6, v7
	v_readlane_b32 s6, v2, 20
	v_readlane_b32 s7, v4, 20
	v_readfirstlane_b32 s12, v7
	v_add_f32_e32 v8, s6, v8
	v_max_f32_e32 v7, s7, v7
	v_writelane_b32 v21, s12, 20
	v_add_f32_e32 v7, s6, v7
	v_readlane_b32 s6, v2, 21
	v_readlane_b32 s7, v4, 21
	v_readfirstlane_b32 s12, v7
	v_add_f32_e32 v8, s6, v8
	v_max_f32_e32 v7, s7, v7
	v_writelane_b32 v21, s12, 21
	v_add_f32_e32 v7, s6, v7
	v_readlane_b32 s6, v2, 22
	v_readlane_b32 s7, v4, 22
	v_readfirstlane_b32 s12, v7
	v_add_f32_e32 v8, s6, v8
	v_max_f32_e32 v7, s7, v7
	v_writelane_b32 v21, s12, 22
	v_add_f32_e32 v7, s6, v7
	v_readlane_b32 s6, v2, 23
	v_readlane_b32 s7, v4, 23
	v_readfirstlane_b32 s12, v7
	v_add_f32_e32 v8, s6, v8
	v_max_f32_e32 v7, s7, v7
	v_writelane_b32 v21, s12, 23
	v_add_f32_e32 v7, s6, v7
	v_add_f32_e32 v10, v9, v8
	v_sub_f32_e32 v11, v10, v7
	v_mul_f32_e32 v10, 0x3fb8aa3b, v11
	v_fma_f32 v12, v11, s8, -v10
	v_rndne_f32_e32 v13, v10
	v_fmac_f32_e32 v12, 0x32a5705f, v11
	v_sub_f32_e32 v10, v10, v13
	v_add_f32_e32 v10, v10, v12
	v_cvt_i32_f32_e32 v12, v13
	v_exp_f32_e32 v10, v10
	v_cmp_ngt_f32_e64 s[2:3], s9, v11
	v_ldexp_f32 v12, v10, v12
	s_nop 0
	v_cndmask_b32_e64 v12, 0, v12, s[2:3]
	v_cmp_nlt_f32_e64 s[2:3], s10, v11
	v_mov_b32_e32 v8, 0
	s_nop 0
	v_cndmask_b32_e64 v10, v6, v12, s[2:3]
	v_mov_b32_e32 v9, v7
	s_nop 0
	v_readfirstlane_b32 s13, v10
	s_nop 1
	v_writelane_b32 v22, s13, 10
	v_readlane_b32 s6, v2, 24
	v_readlane_b32 s7, v4, 24
	v_readfirstlane_b32 s12, v7
	v_add_f32_e32 v8, s6, v8
	v_max_f32_e32 v7, s7, v7
	v_writelane_b32 v21, s12, 24
	v_add_f32_e32 v7, s6, v7
	v_readlane_b32 s6, v2, 25
	v_readlane_b32 s7, v4, 25
	v_readfirstlane_b32 s12, v7
	v_add_f32_e32 v8, s6, v8
	v_max_f32_e32 v7, s7, v7
	v_writelane_b32 v21, s12, 25
	v_add_f32_e32 v7, s6, v7
	v_readlane_b32 s6, v2, 26
	v_readlane_b32 s7, v4, 26
	v_readfirstlane_b32 s12, v7
	v_add_f32_e32 v8, s6, v8
	v_max_f32_e32 v7, s7, v7
	v_writelane_b32 v21, s12, 26
	v_add_f32_e32 v7, s6, v7
	v_readlane_b32 s6, v2, 27
	v_readlane_b32 s7, v4, 27
	v_readfirstlane_b32 s12, v7
	v_add_f32_e32 v8, s6, v8
	v_max_f32_e32 v7, s7, v7
	v_writelane_b32 v21, s12, 27
	v_add_f32_e32 v7, s6, v7
	v_readlane_b32 s6, v2, 28
	v_readlane_b32 s7, v4, 28
	v_readfirstlane_b32 s12, v7
	v_add_f32_e32 v8, s6, v8
	v_max_f32_e32 v7, s7, v7
	v_writelane_b32 v21, s12, 28
	v_add_f32_e32 v7, s6, v7
	v_readlane_b32 s6, v2, 29
	v_readlane_b32 s7, v4, 29
	v_readfirstlane_b32 s12, v7
	v_add_f32_e32 v8, s6, v8
	v_max_f32_e32 v7, s7, v7
	v_writelane_b32 v21, s12, 29
	v_add_f32_e32 v7, s6, v7
	v_readlane_b32 s6, v2, 30
	v_readlane_b32 s7, v4, 30
	v_readfirstlane_b32 s12, v7
	v_add_f32_e32 v8, s6, v8
	v_max_f32_e32 v7, s7, v7
	v_writelane_b32 v21, s12, 30
	v_add_f32_e32 v7, s6, v7
	v_readlane_b32 s6, v2, 31
	v_readlane_b32 s7, v4, 31
	v_readfirstlane_b32 s12, v7
	v_add_f32_e32 v8, s6, v8
	v_max_f32_e32 v7, s7, v7
	v_writelane_b32 v21, s12, 31
	v_add_f32_e32 v7, s6, v7
	v_add_f32_e32 v10, v9, v8
	v_sub_f32_e32 v11, v10, v7
	v_mul_f32_e32 v10, 0x3fb8aa3b, v11
	v_fma_f32 v12, v11, s8, -v10
	v_rndne_f32_e32 v13, v10
	v_fmac_f32_e32 v12, 0x32a5705f, v11
	v_sub_f32_e32 v10, v10, v13
	v_add_f32_e32 v10, v10, v12
	v_cvt_i32_f32_e32 v12, v13
	v_exp_f32_e32 v10, v10
	v_cmp_ngt_f32_e64 s[2:3], s9, v11
	v_ldexp_f32 v12, v10, v12
	s_nop 0
	v_cndmask_b32_e64 v12, 0, v12, s[2:3]
	v_cmp_nlt_f32_e64 s[2:3], s10, v11
	v_mov_b32_e32 v8, 0
	s_nop 0
	v_cndmask_b32_e64 v10, v6, v12, s[2:3]
	v_mov_b32_e32 v9, v7
	s_nop 0
	v_readfirstlane_b32 s13, v10
	s_nop 1
	v_writelane_b32 v22, s13, 11
	v_readlane_b32 s6, v2, 32
	v_readlane_b32 s7, v4, 32
	v_readfirstlane_b32 s12, v7
	v_add_f32_e32 v8, s6, v8
	v_max_f32_e32 v7, s7, v7
	v_writelane_b32 v21, s12, 32
	v_add_f32_e32 v7, s6, v7
	v_readlane_b32 s6, v2, 33
	v_readlane_b32 s7, v4, 33
	v_readfirstlane_b32 s12, v7
	v_add_f32_e32 v8, s6, v8
	v_max_f32_e32 v7, s7, v7
	v_writelane_b32 v21, s12, 33
	v_add_f32_e32 v7, s6, v7
	v_readlane_b32 s6, v2, 34
	v_readlane_b32 s7, v4, 34
	v_readfirstlane_b32 s12, v7
	v_add_f32_e32 v8, s6, v8
	v_max_f32_e32 v7, s7, v7
	v_writelane_b32 v21, s12, 34
	v_add_f32_e32 v7, s6, v7
	v_readlane_b32 s6, v2, 35
	v_readlane_b32 s7, v4, 35
	v_readfirstlane_b32 s12, v7
	v_add_f32_e32 v8, s6, v8
	v_max_f32_e32 v7, s7, v7
	v_writelane_b32 v21, s12, 35
	v_add_f32_e32 v7, s6, v7
	v_readlane_b32 s6, v2, 36
	v_readlane_b32 s7, v4, 36
	v_readfirstlane_b32 s12, v7
	v_add_f32_e32 v8, s6, v8
	v_max_f32_e32 v7, s7, v7
	v_writelane_b32 v21, s12, 36
	v_add_f32_e32 v7, s6, v7
	v_readlane_b32 s6, v2, 37
	v_readlane_b32 s7, v4, 37
	v_readfirstlane_b32 s12, v7
	v_add_f32_e32 v8, s6, v8
	v_max_f32_e32 v7, s7, v7
	v_writelane_b32 v21, s12, 37
	v_add_f32_e32 v7, s6, v7
	v_readlane_b32 s6, v2, 38
	v_readlane_b32 s7, v4, 38
	v_readfirstlane_b32 s12, v7
	v_add_f32_e32 v8, s6, v8
	v_max_f32_e32 v7, s7, v7
	v_writelane_b32 v21, s12, 38
	v_add_f32_e32 v7, s6, v7
	v_readlane_b32 s6, v2, 39
	v_readlane_b32 s7, v4, 39
	v_readfirstlane_b32 s12, v7
	v_add_f32_e32 v8, s6, v8
	v_max_f32_e32 v7, s7, v7
	v_writelane_b32 v21, s12, 39
	v_add_f32_e32 v7, s6, v7
	v_add_f32_e32 v10, v9, v8
	v_sub_f32_e32 v11, v10, v7
	v_mul_f32_e32 v10, 0x3fb8aa3b, v11
	v_fma_f32 v12, v11, s8, -v10
	v_rndne_f32_e32 v13, v10
	v_fmac_f32_e32 v12, 0x32a5705f, v11
	v_sub_f32_e32 v10, v10, v13
	v_add_f32_e32 v10, v10, v12
	v_cvt_i32_f32_e32 v12, v13
	v_exp_f32_e32 v10, v10
	v_cmp_ngt_f32_e64 s[2:3], s9, v11
	v_ldexp_f32 v12, v10, v12
	s_nop 0
	v_cndmask_b32_e64 v12, 0, v12, s[2:3]
	v_cmp_nlt_f32_e64 s[2:3], s10, v11
	v_mov_b32_e32 v8, 0
	s_nop 0
	v_cndmask_b32_e64 v10, v6, v12, s[2:3]
	v_mov_b32_e32 v9, v7
	s_nop 0
	v_readfirstlane_b32 s13, v10
	s_nop 1
	v_writelane_b32 v22, s13, 12
	v_readlane_b32 s6, v2, 40
	v_readlane_b32 s7, v4, 40
	v_readfirstlane_b32 s12, v7
	v_add_f32_e32 v8, s6, v8
	v_max_f32_e32 v7, s7, v7
	v_writelane_b32 v21, s12, 40
	v_add_f32_e32 v7, s6, v7
	v_readlane_b32 s6, v2, 41
	v_readlane_b32 s7, v4, 41
	v_readfirstlane_b32 s12, v7
	v_add_f32_e32 v8, s6, v8
	v_max_f32_e32 v7, s7, v7
	v_writelane_b32 v21, s12, 41
	v_add_f32_e32 v7, s6, v7
	v_readlane_b32 s6, v2, 42
	v_readlane_b32 s7, v4, 42
	v_readfirstlane_b32 s12, v7
	v_add_f32_e32 v8, s6, v8
	v_max_f32_e32 v7, s7, v7
	v_writelane_b32 v21, s12, 42
	v_add_f32_e32 v7, s6, v7
	v_readlane_b32 s6, v2, 43
	v_readlane_b32 s7, v4, 43
	v_readfirstlane_b32 s12, v7
	v_add_f32_e32 v8, s6, v8
	v_max_f32_e32 v7, s7, v7
	v_writelane_b32 v21, s12, 43
	v_add_f32_e32 v7, s6, v7
	v_readlane_b32 s6, v2, 44
	v_readlane_b32 s7, v4, 44
	v_readfirstlane_b32 s12, v7
	v_add_f32_e32 v8, s6, v8
	v_max_f32_e32 v7, s7, v7
	v_writelane_b32 v21, s12, 44
	v_add_f32_e32 v7, s6, v7
	v_readlane_b32 s6, v2, 45
	v_readlane_b32 s7, v4, 45
	v_readfirstlane_b32 s12, v7
	v_add_f32_e32 v8, s6, v8
	v_max_f32_e32 v7, s7, v7
	v_writelane_b32 v21, s12, 45
	v_add_f32_e32 v7, s6, v7
	v_readlane_b32 s6, v2, 46
	v_readlane_b32 s7, v4, 46
	v_readfirstlane_b32 s12, v7
	v_add_f32_e32 v8, s6, v8
	v_max_f32_e32 v7, s7, v7
	v_writelane_b32 v21, s12, 46
	v_add_f32_e32 v7, s6, v7
	v_readlane_b32 s6, v2, 47
	v_readlane_b32 s7, v4, 47
	v_readfirstlane_b32 s12, v7
	v_add_f32_e32 v8, s6, v8
	v_max_f32_e32 v7, s7, v7
	v_writelane_b32 v21, s12, 47
	v_add_f32_e32 v7, s6, v7
	v_add_f32_e32 v10, v9, v8
	v_sub_f32_e32 v11, v10, v7
	v_mul_f32_e32 v10, 0x3fb8aa3b, v11
	v_fma_f32 v12, v11, s8, -v10
	v_rndne_f32_e32 v13, v10
	v_fmac_f32_e32 v12, 0x32a5705f, v11
	v_sub_f32_e32 v10, v10, v13
	v_add_f32_e32 v10, v10, v12
	v_cvt_i32_f32_e32 v12, v13
	v_exp_f32_e32 v10, v10
	v_cmp_ngt_f32_e64 s[2:3], s9, v11
	v_ldexp_f32 v12, v10, v12
	s_nop 0
	v_cndmask_b32_e64 v12, 0, v12, s[2:3]
	v_cmp_nlt_f32_e64 s[2:3], s10, v11
	v_mov_b32_e32 v8, 0
	s_nop 0
	v_cndmask_b32_e64 v10, v6, v12, s[2:3]
	v_mov_b32_e32 v9, v7
	s_nop 0
	v_readfirstlane_b32 s13, v10
	s_nop 1
	v_writelane_b32 v22, s13, 13
	v_readlane_b32 s6, v2, 48
	v_readlane_b32 s7, v4, 48
	v_readfirstlane_b32 s12, v7
	v_add_f32_e32 v8, s6, v8
	v_max_f32_e32 v7, s7, v7
	v_writelane_b32 v21, s12, 48
	v_add_f32_e32 v7, s6, v7
	v_readlane_b32 s6, v2, 49
	v_readlane_b32 s7, v4, 49
	v_readfirstlane_b32 s12, v7
	v_add_f32_e32 v8, s6, v8
	v_max_f32_e32 v7, s7, v7
	v_writelane_b32 v21, s12, 49
	v_add_f32_e32 v7, s6, v7
	v_readlane_b32 s6, v2, 50
	v_readlane_b32 s7, v4, 50
	v_readfirstlane_b32 s12, v7
	v_add_f32_e32 v8, s6, v8
	v_max_f32_e32 v7, s7, v7
	v_writelane_b32 v21, s12, 50
	v_add_f32_e32 v7, s6, v7
	v_readlane_b32 s6, v2, 51
	v_readlane_b32 s7, v4, 51
	v_readfirstlane_b32 s12, v7
	v_add_f32_e32 v8, s6, v8
	v_max_f32_e32 v7, s7, v7
	v_writelane_b32 v21, s12, 51
	v_add_f32_e32 v7, s6, v7
	v_readlane_b32 s6, v2, 52
	v_readlane_b32 s7, v4, 52
	v_readfirstlane_b32 s12, v7
	v_add_f32_e32 v8, s6, v8
	v_max_f32_e32 v7, s7, v7
	v_writelane_b32 v21, s12, 52
	v_add_f32_e32 v7, s6, v7
	v_readlane_b32 s6, v2, 53
	v_readlane_b32 s7, v4, 53
	v_readfirstlane_b32 s12, v7
	v_add_f32_e32 v8, s6, v8
	v_max_f32_e32 v7, s7, v7
	v_writelane_b32 v21, s12, 53
	v_add_f32_e32 v7, s6, v7
	v_readlane_b32 s6, v2, 54
	v_readlane_b32 s7, v4, 54
	v_readfirstlane_b32 s12, v7
	v_add_f32_e32 v8, s6, v8
	v_max_f32_e32 v7, s7, v7
	v_writelane_b32 v21, s12, 54
	v_add_f32_e32 v7, s6, v7
	v_readlane_b32 s6, v2, 55
	v_readlane_b32 s7, v4, 55
	v_readfirstlane_b32 s12, v7
	v_add_f32_e32 v8, s6, v8
	v_max_f32_e32 v7, s7, v7
	v_writelane_b32 v21, s12, 55
	v_add_f32_e32 v7, s6, v7
	v_add_f32_e32 v10, v9, v8
	v_sub_f32_e32 v11, v10, v7
	v_mul_f32_e32 v10, 0x3fb8aa3b, v11
	v_fma_f32 v12, v11, s8, -v10
	v_rndne_f32_e32 v13, v10
	v_fmac_f32_e32 v12, 0x32a5705f, v11
	v_sub_f32_e32 v10, v10, v13
	v_add_f32_e32 v10, v10, v12
	v_cvt_i32_f32_e32 v12, v13
	v_exp_f32_e32 v10, v10
	v_cmp_ngt_f32_e64 s[2:3], s9, v11
	v_ldexp_f32 v12, v10, v12
	s_nop 0
	v_cndmask_b32_e64 v12, 0, v12, s[2:3]
	v_cmp_nlt_f32_e64 s[2:3], s10, v11
	v_mov_b32_e32 v8, 0
	s_nop 0
	v_cndmask_b32_e64 v10, v6, v12, s[2:3]
	v_mov_b32_e32 v9, v7
	s_nop 0
	v_readfirstlane_b32 s13, v10
	s_nop 1
	v_writelane_b32 v22, s13, 14
	v_readlane_b32 s6, v2, 56
	v_readlane_b32 s7, v4, 56
	v_readfirstlane_b32 s12, v7
	v_add_f32_e32 v8, s6, v8
	v_max_f32_e32 v7, s7, v7
	v_writelane_b32 v21, s12, 56
	v_add_f32_e32 v7, s6, v7
	v_readlane_b32 s6, v2, 57
	v_readlane_b32 s7, v4, 57
	v_readfirstlane_b32 s12, v7
	v_add_f32_e32 v8, s6, v8
	v_max_f32_e32 v7, s7, v7
	v_writelane_b32 v21, s12, 57
	v_add_f32_e32 v7, s6, v7
	v_readlane_b32 s6, v2, 58
	v_readlane_b32 s7, v4, 58
	v_readfirstlane_b32 s12, v7
	v_add_f32_e32 v8, s6, v8
	v_max_f32_e32 v7, s7, v7
	v_writelane_b32 v21, s12, 58
	v_add_f32_e32 v7, s6, v7
	v_readlane_b32 s6, v2, 59
	v_readlane_b32 s7, v4, 59
	v_readfirstlane_b32 s12, v7
	v_add_f32_e32 v8, s6, v8
	v_max_f32_e32 v7, s7, v7
	v_writelane_b32 v21, s12, 59
	v_add_f32_e32 v7, s6, v7
	v_readlane_b32 s6, v2, 60
	v_readlane_b32 s7, v4, 60
	v_readfirstlane_b32 s12, v7
	v_add_f32_e32 v8, s6, v8
	v_max_f32_e32 v7, s7, v7
	v_writelane_b32 v21, s12, 60
	v_add_f32_e32 v7, s6, v7
	v_readlane_b32 s6, v2, 61
	v_readlane_b32 s7, v4, 61
	v_readfirstlane_b32 s12, v7
	v_add_f32_e32 v8, s6, v8
	v_max_f32_e32 v7, s7, v7
	v_writelane_b32 v21, s12, 61
	v_add_f32_e32 v7, s6, v7
	v_readlane_b32 s6, v2, 62
	v_readlane_b32 s7, v4, 62
	v_readfirstlane_b32 s12, v7
	v_add_f32_e32 v8, s6, v8
	v_max_f32_e32 v7, s7, v7
	v_writelane_b32 v21, s12, 62
	v_add_f32_e32 v7, s6, v7
	v_readlane_b32 s6, v2, 63
	v_readlane_b32 s7, v4, 63
	v_readfirstlane_b32 s12, v7
	v_add_f32_e32 v8, s6, v8
	v_max_f32_e32 v7, s7, v7
	v_writelane_b32 v21, s12, 63
	v_add_f32_e32 v7, s6, v7
	v_add_f32_e32 v10, v9, v8
	v_sub_f32_e32 v11, v10, v7
	v_mul_f32_e32 v10, 0x3fb8aa3b, v11
	v_fma_f32 v12, v11, s8, -v10
	v_rndne_f32_e32 v13, v10
	v_fmac_f32_e32 v12, 0x32a5705f, v11
	v_sub_f32_e32 v10, v10, v13
	v_add_f32_e32 v10, v10, v12
	v_cvt_i32_f32_e32 v12, v13
	v_exp_f32_e32 v10, v10
	v_cmp_ngt_f32_e64 s[2:3], s9, v11
	v_ldexp_f32 v12, v10, v12
	s_nop 0
	v_cndmask_b32_e64 v12, 0, v12, s[2:3]
	v_cmp_nlt_f32_e64 s[2:3], s10, v11
	v_mov_b32_e32 v8, 0
	s_nop 0
	v_cndmask_b32_e64 v10, v6, v12, s[2:3]
	v_mov_b32_e32 v9, v7
	s_nop 0
	v_readfirstlane_b32 s13, v10
	s_nop 1
	v_writelane_b32 v22, s13, 15
	v_mbcnt_lo_u32_b32 v23, -1, 0
	v_mbcnt_hi_u32_b32 v23, -1, v23
	v_lshlrev_b32_e32 v23, 2, v23
	s_add_i32 s12, s4, 0x60000
	s_ashr_i32 s13, s12, 31
	s_lshl_b64 s[12:13], s[12:13], 2
	s_add_u32 s12, s48, s12
	s_addc_u32 s13, s49, s13
	global_store_dword v23, v20, s[12:13]
	global_store_dword v23, v21, s[12:13] offset:256
	s_mov_b32 s2, s5
	s_ashr_i32 s3, s2, 31
	s_lshl_b64 s[2:3], s[2:3], 2
	s_add_u32 s2, s48, s2
	s_addc_u32 s3, s49, s3
	s_mov_b64 s[6:7], exec
	s_mov_b64 exec, 0xffff
	global_store_dword v23, v22, s[2:3]
	s_mov_b64 exec, s[6:7]
